# baseline (speedup 1.0000x reference)
; DI int opq(int x) { asm volatile("" : "+v"(x)); return x; }
; DI void indexer_item(const Params& p, int b, int qt16, char* smem) {
;   u16* iqs = (u16*)smem;
;   float* wls = (float*)(smem + 16 * 2080);
;   const int tid = opq(threadIdx.x), lane = tid & 63, wid = tid >> 6, l15 = lane & 15, g4 = lane >> 4;
;   const int t0 = qt16 * 16;
;   const u16* base = p.PROJ + (long)b * SEQ * PW;
;   float* scr = p.SCR + (long)blockIdx.x * 16 * SEQ;
; #pragma unroll
;   for (int i = 0; i < 4; ++i) {
;     const int v = tid + NT * i, q = v >> 7, c = v & 127;
;     *(u32x4*)(iqs + q * 1040 + c * 8) = *(const u32x4*)(base + (long)(t0 + q) * PW + DIQ + c * 8);
;   }
;   if (tid < 256) {
;     const int q = tid >> 4, h = tid & 15;
;     wls[tid] = __uint_as_float(((u32)base[(long)(t0 + q) * PW + DIW + h]) << 16);
;   }
;   __syncthreads();
;   const int nkb = (t0 + 16 + 63) >> 6;
;   bf16x8 kfn[4][2];
;   if (wid < nkb) {
; #pragma unroll
;     for (int t = 0; t < 4; ++t)
; #pragma unroll
;       for (int ks = 0; ks < 2; ++ks)
;         kfn[t][ks] = *(const bf16x8*)(base + (long)(wid * 64 + t * 16 + l15) * PW + DIK + ks * 32 + g4 * 8);
;   }
;   for (int kb = wid; kb < nkb; kb += 8) {
;     bf16x8 kf[4][2];
; #pragma unroll
;     for (int t = 0; t < 4; ++t)
; #pragma unroll
;       for (int ks = 0; ks < 2; ++ks) kf[t][ks] = kfn[t][ks];
.Lq_common_2:
	ds_read_b32 v0, v1 offset:48
	s_movk_i32 s0, 0x3ff
	s_waitcnt lgkmcnt(0)
	v_cmp_lt_i32_e32 vcc, s0, v0
	s_mov_b64 s[0:1], -1
	s_cbranch_vccnz .LBB0_309
	v_lshlrev_b32_e32 v2, 2, v0
	v_lshlrev_b32_e32 v0, 12, v0
	v_mov_b32_e32 v34, v188
	v_and_b32_e32 v2, -16, v2
	v_and_b32_e32 v86, 0x3000, v0
	v_readlane_b32 s0, v249, 6
	s_waitcnt vmcnt(23)
	v_sub_u32_e32 v99, 0xff0, v2
	v_mul_lo_u32 v0, v86, s75
	v_readlane_b32 s1, v249, 7
	v_ashrrev_i32_e32 v3, 7, v34
	v_add_u32_e32 v4, v3, v99
	v_lshl_add_u64 v[88:89], s[0:1], 0, v[0:1]
	v_lshlrev_b32_e32 v0, 4, v34
	v_readlane_b32 s2, v249, 8
	v_and_b32_e32 v0, 0x7f0, v0
	v_mad_i64_i32 v[4:5], s[0:1], v4, s75, v[88:89]
	v_lshl_add_u64 v[4:5], v[4:5], 0, v[0:1]
	s_movk_i32 s2, 0x1000
	v_add_co_u32_e32 v4, vcc, s2, v4
	v_readlane_b32 s3, v249, 9
	s_nop 0
	v_addc_co_u32_e32 v5, vcc, 0, v5, vcc
	global_load_dwordx4 v[110:113], v[4:5], off offset:2048
	v_add_u32_e32 v8, 64, v0
	s_movk_i32 s3, 0x820
	v_mad_u64_u32 v[126:127], s[0:1], v3, s3, v[8:9]
	v_add_u32_e32 v3, 0x200, v34
	v_ashrrev_i32_e32 v3, 7, v3
	v_and_b32_e32 v87, 15, v34
	v_readlane_b32 s4, v249, 10
	v_readlane_b32 s5, v249, 11
	v_readlane_b32 s6, v249, 12
	v_readlane_b32 s7, v249, 13
	v_add_u32_e32 v4, v3, v99
	v_mad_i64_i32 v[4:5], s[0:1], v4, s75, v[88:89]
	v_lshl_add_u64 v[4:5], v[4:5], 0, v[0:1]
	v_add_co_u32_e32 v4, vcc, s2, v4
	v_mad_u64_u32 v[128:129], s[0:1], v3, s3, v[8:9]
	s_nop 0
	v_addc_co_u32_e32 v5, vcc, 0, v5, vcc
	global_load_dwordx4 v[114:117], v[4:5], off offset:2048
	v_add_u32_e32 v3, 0x400, v34
	v_ashrrev_i32_e32 v3, 7, v3
	v_add_u32_e32 v4, v3, v99
	v_mad_i64_i32 v[4:5], s[0:1], v4, s75, v[88:89]
	v_lshl_add_u64 v[4:5], v[4:5], 0, v[0:1]
	v_add_co_u32_e32 v4, vcc, s2, v4
	v_mad_u64_u32 v[10:11], s[0:1], v3, s3, v[8:9]
	s_nop 0
	v_addc_co_u32_e32 v5, vcc, 0, v5, vcc
	global_load_dwordx4 v[118:121], v[4:5], off offset:2048
	v_add_u32_e32 v3, 0x600, v34
	v_ashrrev_i32_e32 v3, 7, v3
	v_mad_u64_u32 v[8:9], s[0:1], v3, s3, v[8:9]
	v_add_u32_e32 v4, v3, v99
	v_mad_i64_i32 v[4:5], s[0:1], v4, s75, v[88:89]
	v_lshl_add_u64 v[4:5], v[4:5], 0, v[0:1]
	v_add_co_u32_e32 v4, vcc, 0x1000, v4
	s_movk_i32 s0, 0x100
	s_nop 0
	v_addc_co_u32_e32 v5, vcc, 0, v5, vcc
	global_load_dwordx4 v[122:125], v[4:5], off offset:2048
	v_cmp_gt_i32_e32 vcc, s0, v34
	s_and_saveexec_b64 s[0:1], vcc
	s_cbranch_execz .LBB0_315
	v_ashrrev_i32_e32 v0, 4, v34
	v_add_u32_e32 v0, v0, v99
	v_mad_i64_i32 v[4:5], s[2:3], v0, s75, v[88:89]
	v_lshlrev_b32_e32 v0, 1, v87
	v_lshl_add_u64 v[4:5], v[4:5], 0, v[0:1]
	v_add_co_u32_e32 v4, vcc, 0x2000, v4
	v_lshl_add_u32 v3, v34, 2, 64
	s_nop 0
	v_addc_co_u32_e32 v5, vcc, 0, v5, vcc
	global_load_ushort v0, v[4:5], off offset:1408
	s_waitcnt vmcnt(0)
	v_lshlrev_b32_e32 v0, 16, v0
	ds_write_b32 v3, v0 offset:33280
.LBB0_315:
	s_or_b64 exec, exec, s[0:1]
	s_waitcnt vmcnt(3)
	ds_write_b128 v126, v[110:113]
	s_waitcnt vmcnt(2)
	ds_write_b128 v128, v[114:117]
	s_waitcnt vmcnt(1)
	ds_write_b128 v10, v[118:121]
	s_waitcnt vmcnt(0)
	ds_write_b128 v8, v[122:125]
	v_sub_u32_e32 v0, 0x1030, v2
	v_ashrrev_i32_e32 v98, 6, v34
	v_lshrrev_b32_e32 v100, 6, v0
	v_and_b32_e32 v102, 63, v34
	v_cmp_lt_i32_e32 vcc, v98, v100
	s_waitcnt lgkmcnt(0)
	s_barrier
	s_and_saveexec_b64 s[2:3], vcc
	s_cbranch_execz .LBB0_322
	v_and_b32_e32 v18, 0xffffffcf, v34
	v_mad_i64_i32 v[2:3], s[0:1], v18, s75, v[88:89]
	v_and_b32_e32 v0, 48, v102
	v_lshl_add_u64 v[2:3], v[2:3], 0, v[0:1]
	s_mov_b64 s[4:5], 0x2500
	v_or_b32_e32 v10, 16, v18
	v_lshl_add_u64 v[6:7], v[2:3], 0, s[4:5]
	v_add_co_u32_e32 v2, vcc, 0x2000, v2
	v_mad_i64_i32 v[10:11], s[0:1], v10, s75, v[88:89]
	s_nop 0
	v_addc_co_u32_e32 v3, vcc, 0, v3, vcc
	v_lshl_add_u64 v[10:11], v[10:11], 0, v[0:1]
	v_or_b32_e32 v18, 32, v18
	v_lshl_add_u64 v[14:15], v[10:11], 0, s[4:5]
	v_add_co_u32_e32 v10, vcc, 0x2000, v10
	v_mad_i64_i32 v[18:19], s[0:1], v18, s75, v[88:89]
	s_nop 0
	v_addc_co_u32_e32 v11, vcc, 0, v11, vcc
	v_lshl_add_u64 v[18:19], v[18:19], 0, v[0:1]
	v_or_b32_e32 v26, 48, v34
	v_lshl_add_u64 v[22:23], v[18:19], 0, s[4:5]
	v_add_co_u32_e32 v18, vcc, 0x2000, v18
	v_mad_i64_i32 v[26:27], s[0:1], v26, s75, v[88:89]
	s_nop 0
	v_addc_co_u32_e32 v19, vcc, 0, v19, vcc
	v_lshl_add_u64 v[26:27], v[26:27], 0, v[0:1]
	v_lshl_add_u64 v[30:31], v[26:27], 0, s[4:5]
	v_add_co_u32_e32 v26, vcc, 0x2000, v26
	global_load_dwordx4 v[2:5], v[2:3], off offset:1280
	s_nop 0
	global_load_dwordx4 v[6:9], v[6:7], off offset:64
	v_addc_co_u32_e32 v27, vcc, 0, v27, vcc
	global_load_dwordx4 v[10:13], v[10:11], off offset:1280
	s_nop 0
	global_load_dwordx4 v[14:17], v[14:15], off offset:64
	s_nop 0
	global_load_dwordx4 v[18:21], v[18:19], off offset:1280
	s_nop 0
	global_load_dwordx4 v[22:25], v[22:23], off offset:64
	s_nop 0
	global_load_dwordx4 v[26:29], v[26:27], off offset:1280
	s_nop 0
	global_load_dwordx4 v[30:33], v[30:31], off offset:64
	v_lshrrev_b32_e32 v36, 1, v102
	v_and_b32_e32 v38, 48, v34
	v_lshlrev_b32_e32 v34, 14, v87
	v_mov_b32_e32 v35, v1
	v_mul_u32_u24_e32 v37, 0x820, v87
	v_mul_i32_i24_e32 v39, 0xfffff820, v87
	v_and_b32_e32 v36, 24, v36
	v_lshl_add_u64 v[34:35], s[96:97], 0, v[34:35]
	v_readlane_b32 s0, v249, 28
	v_add3_u32 v101, 64, v37, v38
	v_lshl_add_u64 v[90:91], v[34:35], 0, v[0:1]
	v_add3_u32 v103, v37, v39, s0
	v_lshlrev_b32_e32 v0, 1, v36
	s_mov_b64 s[4:5], 0
	v_mov_b32_e32 v104, v98
	s_waitcnt vmcnt(7)
	v_mov_b64_e32 v[36:37], v[4:5]
	s_waitcnt vmcnt(6)
	v_mov_b64_e32 v[40:41], v[8:9]
	v_mov_b64_e32 v[34:35], v[2:3]
	s_waitcnt vmcnt(5)
	v_mov_b64_e32 v[44:45], v[12:13]
	s_waitcnt vmcnt(4)
	v_mov_b64_e32 v[48:49], v[16:17]
	s_waitcnt vmcnt(3)
	v_mov_b64_e32 v[52:53], v[20:21]
	s_waitcnt vmcnt(2)
	v_mov_b64_e32 v[56:57], v[24:25]
	s_waitcnt vmcnt(1)
	v_mov_b64_e32 v[60:61], v[28:29]
	s_waitcnt vmcnt(0)
	v_mov_b64_e32 v[64:65], v[32:33]
	v_mov_b64_e32 v[38:39], v[6:7]
	v_mov_b64_e32 v[42:43], v[10:11]
	v_mov_b64_e32 v[46:47], v[14:15]
	v_mov_b64_e32 v[50:51], v[18:19]
	v_mov_b64_e32 v[54:55], v[22:23]
	v_mov_b64_e32 v[58:59], v[26:27]
	v_mov_b64_e32 v[62:63], v[30:31]
